# combination of all individually-neutral latency/issue-slot edits on top of v23: P0 cvt_pk + scale-load batching, seam-1 arrive deferral, hook prefetch, barrier TOP polling, P6 tail prefetch, no acc ze
# baseline (speedup 1.0000x reference)
; #define PG8_STAGE(bufoff, gbase, voff) do { _Pragma("unroll") for (int _i = 0; _i < 2; ++_i) \
;         __builtin_amdgcn_global_load_lds((const unsigned*)((const char*)(gbase) + (voff)[_i]), (PG8_LAS unsigned*)(lds + (bufoff) + ldsw + _i * 8192), 16, 0, 0); } while (0)
; #define PG8_LDA(dst, b, h) do { _Pragma("unroll") for (int m = 0; m < 4; ++m) _Pragma("unroll") for (int k = 0; k < 2; ++k) dst[m][k] = *(const PG8_LAS bf16x8*)(lds + PG8_SA(b, h) + aoff + m * 2048 + k * 1024); } while (0)
; #define PG8_LDB(dst, b, h) do { _Pragma("unroll") for (int n = 0; n < 2; ++n) _Pragma("unroll") for (int k = 0; k < 2; ++k) dst[n][k] = *(const PG8_LAS bf16x8*)(lds + PG8_SB(b, h) + boff + n * 2048 + k * 1024); } while (0)
; #define PG8_MMA(ai, bj, At, Bt) do { __builtin_amdgcn_s_setprio(1); _Pragma("unroll") for (int m = 0; m < 4; ++m) _Pragma("unroll") for (int n = 0; n < 2; ++n) _Pragma("unroll") for (int k = 0; k < 2; ++k) \
;         acc[ai][bj][m][n] = __builtin_amdgcn_mfma_f32_16x16x32_bf16(Bt[n][k], At[m][k], acc[ai][bj][m][n], 0, 0, 0); __builtin_amdgcn_s_setprio(0); } while (0)
; #define PG8_WAIT_V(n) asm volatile("s_waitcnt vmcnt(" #n ")" ::: "memory")
; #define PG8_WAIT_L(n) asm volatile("s_waitcnt lgkmcnt(" #n ")" ::: "memory")
; #define PG8_BAR __builtin_amdgcn_s_barrier()
; #define PG8_SCHED __builtin_amdgcn_sched_barrier(0)
; template <class Epi, class Sched, bool ALIGN_EPI = false, bool SP2 = false>
; __device__ __forceinline__ void gemm_phase(PG8_LAS unsigned char* lds, const Gemm g, const Sched& S, const Epi& E, int wid_in) {
;     ...
;     f32x4 acc[2][2][4][2];
; #pragma unroll
;     for (int a = 0; a < 2; ++a)
; #pragma unroll
;         for (int b = 0; b < 2; ++b)
; #pragma unroll
;             for (int m = 0; m < 4; ++m)
; #pragma unroll
;                 for (int n = 0; n < 2; ++n) acc[a][b][m][n] = (f32x4){0.f, 0.f, 0.f, 0.f};
;     ...
;             PG8_LDB(B0, 0, 0); PG8_LDB(B1, 0, 1); PG8_SCHED; PG8_LDA(At, 0, 0); PG8_STAGE(PG8_SA(1, 1), a1 + hstep, voffA);
;             PG8_WAIT_V(8); PG8_WAIT_L(0); PG8_BAR; PG8_MMA(0, 0, At, B0); PG8_MMA(0, 1, At, B1); PG8_BAR; PG8_SCHED;
;             PG8_LDA(At, 0, 1); PG8_STAGE(PG8_SB(0, 0), b2, voffB); PG8_STAGE(PG8_SB(0, 1), b2 + hstep, voffB); PG8_STAGE(PG8_SA(0, 0), a2, voffA);
;             PG8_WAIT_V(8); PG8_WAIT_L(0); PG8_BAR; PG8_MMA(1, 0, At, B0); PG8_MMA(1, 1, At, B1); PG8_BAR; PG8_SCHED;
.LBB0_226:
	s_ashr_i32 s83, s82, 31
	s_lshl_b64 s[84:85], s[82:83], 19
	s_add_u32 s84, s8, s84
	s_addc_u32 s85, s9, s85
	s_and_b64 s[86:87], s[0:1], exec
	s_cselect_b32 s3, s85, s69
	s_cselect_b32 s5, s84, s68
	s_ashr_i32 s81, s80, 31
	s_lshl_b64 s[86:87], s[80:81], 19
	s_add_u32 s86, s13, s86
	s_addc_u32 s87, s33, s87
	s_and_b64 s[90:91], s[0:1], exec
	s_cselect_b32 s81, s87, s89
	s_cselect_b32 s83, s86, s88
	s_add_u32 s68, s68, 0x40080
	s_addc_u32 s69, s69, 0
	s_add_u32 s92, s88, 0x100
	s_addc_u32 s93, s89, 0
	s_mov_b32 s94, -2
	ds_read_b128 v[128:131], v171
	ds_read_b128 v[132:135], v171 offset:1024
	ds_read_b128 v[158:161], v171 offset:2048
	ds_read_b128 v[162:165], v171 offset:3072
	ds_read_b128 v[174:177], v172
	ds_read_b128 v[178:181], v172 offset:1024
	ds_read_b128 v[182:185], v172 offset:2048
	ds_read_b128 v[186:189], v172 offset:3072
	s_add_u32 s88, s68, 0xfffc0080
	s_addc_u32 s89, s69, -1
	s_cmp_eq_u32 s94, 12
	s_cselect_b32 s91, s3, s89
	s_cselect_b32 s90, s5, s88
	s_cselect_b32 s89, s81, s93
	s_cselect_b32 s88, s83, s92
	v_lshl_add_u64 v[166:167], s[68:69], 0, v[150:151]
	s_add_i32 m0, s34, 0xc000
	ds_read_b128 v[190:193], v173
	ds_read_b128 v[194:197], v173 offset:1024
	ds_read_b128 v[198:201], v173 offset:2048
	ds_read_b128 v[202:205], v173 offset:3072
	ds_read_b128 v[206:209], v173 offset:4096
	ds_read_b128 v[210:213], v173 offset:5120
	ds_read_b128 v[214:217], v173 offset:6144
	ds_read_b128 v[218:221], v173 offset:7168
	global_load_lds_dwordx4 v[166:167], off
	v_lshl_add_u64 v[166:167], s[68:69], 0, v[152:153]
	s_add_i32 m0, s34, 0xe000
	s_nop 0
	global_load_lds_dwordx4 v[166:167], off
	s_waitcnt vmcnt(8)
	s_waitcnt lgkmcnt(0)
	s_barrier
	s_setprio 1
	v_mfma_f32_16x16x32_bf16 v[124:127], v[128:131], v[190:193], 0
	v_mfma_f32_16x16x32_bf16 v[120:123], v[158:161], v[190:193], 0
	v_mfma_f32_16x16x32_bf16 v[108:111], v[128:131], v[198:201], 0
	v_mfma_f32_16x16x32_bf16 v[104:107], v[158:161], v[198:201], 0
	v_mfma_f32_16x16x32_bf16 v[92:95], v[128:131], v[206:209], 0
	v_mfma_f32_16x16x32_bf16 v[88:91], v[158:161], v[206:209], 0
	v_mfma_f32_16x16x32_bf16 v[76:79], v[128:131], v[214:217], 0
	v_mfma_f32_16x16x32_bf16 v[72:75], v[158:161], v[214:217], 0
	v_mfma_f32_16x16x32_bf16 v[124:127], v[132:135], v[194:197], v[124:127]
	v_mfma_f32_16x16x32_bf16 v[120:123], v[162:165], v[194:197], v[120:123]
	v_mfma_f32_16x16x32_bf16 v[108:111], v[132:135], v[202:205], v[108:111]
	v_mfma_f32_16x16x32_bf16 v[104:107], v[162:165], v[202:205], v[104:107]
	v_mfma_f32_16x16x32_bf16 v[92:95], v[132:135], v[210:213], v[92:95]
	v_mfma_f32_16x16x32_bf16 v[88:91], v[162:165], v[210:213], v[88:91]
	v_mfma_f32_16x16x32_bf16 v[76:79], v[132:135], v[218:221], v[76:79]
	v_mfma_f32_16x16x32_bf16 v[72:75], v[162:165], v[218:221], v[72:75]
	v_mfma_f32_16x16x32_bf16 v[116:119], v[174:177], v[190:193], 0
	v_mfma_f32_16x16x32_bf16 v[112:115], v[182:185], v[190:193], 0
	v_mfma_f32_16x16x32_bf16 v[100:103], v[174:177], v[198:201], 0
	v_mfma_f32_16x16x32_bf16 v[96:99], v[182:185], v[198:201], 0
	v_mfma_f32_16x16x32_bf16 v[84:87], v[174:177], v[206:209], 0
	v_mfma_f32_16x16x32_bf16 v[80:83], v[182:185], v[206:209], 0
	v_mfma_f32_16x16x32_bf16 v[68:71], v[174:177], v[214:217], 0
	v_mfma_f32_16x16x32_bf16 v[64:67], v[182:185], v[214:217], 0
	v_mfma_f32_16x16x32_bf16 v[116:119], v[178:181], v[194:197], v[116:119]
	v_mfma_f32_16x16x32_bf16 v[112:115], v[186:189], v[194:197], v[112:115]
	v_mfma_f32_16x16x32_bf16 v[100:103], v[178:181], v[202:205], v[100:103]
	v_mfma_f32_16x16x32_bf16 v[96:99], v[186:189], v[202:205], v[96:99]
	v_mfma_f32_16x16x32_bf16 v[84:87], v[178:181], v[210:213], v[84:87]
	v_mfma_f32_16x16x32_bf16 v[80:83], v[186:189], v[210:213], v[80:83]
	v_mfma_f32_16x16x32_bf16 v[68:71], v[178:181], v[218:221], v[68:71]
	v_mfma_f32_16x16x32_bf16 v[64:67], v[186:189], v[218:221], v[64:67]
	s_setprio 0
	s_barrier
	s_add_i32 s95, s70, s12
	v_lshl_add_u64 v[166:167], s[88:89], 0, v[138:139]
	s_mov_b32 m0, s95
	ds_read_b128 v[190:193], v173 offset:16384
	ds_read_b128 v[194:197], v173 offset:17408
	ds_read_b128 v[198:201], v173 offset:18432
	ds_read_b128 v[202:205], v173 offset:19456
	ds_read_b128 v[206:209], v173 offset:20480
	ds_read_b128 v[210:213], v173 offset:21504
	ds_read_b128 v[214:217], v173 offset:22528
	ds_read_b128 v[218:221], v173 offset:23552
	global_load_lds_dwordx4 v[166:167], off
	s_add_i32 m0, s95, 0x2000
	s_add_u32 vcc_lo, s88, 0x40000
	v_lshl_add_u64 v[222:223], s[88:89], 0, v[142:143]
	s_addc_u32 vcc_hi, s89, 0
	s_add_i32 s95, s71, s12
	global_load_lds_dwordx4 v[222:223], off
	v_lshl_add_u64 v[224:225], vcc, 0, v[138:139]
	s_mov_b32 m0, s95
	v_lshl_add_u64 v[226:227], s[90:91], 0, v[140:141]
	global_load_lds_dwordx4 v[224:225], off
	v_lshl_add_u64 v[224:225], vcc, 0, v[142:143]
	s_add_i32 m0, s95, 0x2000
	s_nop 0
	global_load_lds_dwordx4 v[224:225], off
	v_lshl_add_u64 v[224:225], s[90:91], 0, v[136:137]
	s_mov_b32 m0, s34
	s_nop 0
	global_load_lds_dwordx4 v[224:225], off
	s_mov_b32 m0, s35
	s_nop 0
	global_load_lds_dwordx4 v[226:227], off
	s_waitcnt vmcnt(8)
	s_waitcnt lgkmcnt(0)
	s_barrier
; #define PG8_STAGE(bufoff, gbase, voff) do { _Pragma("unroll") for (int _i = 0; _i < 2; ++_i) \
;         __builtin_amdgcn_global_load_lds((const unsigned*)((const char*)(gbase) + (voff)[_i]), (PG8_LAS unsigned*)(lds + (bufoff) + ldsw + _i * 8192), 16, 0, 0); } while (0)
; #define PG8_LDA(dst, b, h) do { _Pragma("unroll") for (int m = 0; m < 4; ++m) _Pragma("unroll") for (int k = 0; k < 2; ++k) dst[m][k] = *(const PG8_LAS bf16x8*)(lds + PG8_SA(b, h) + aoff + m * 2048 + k * 1024); } while (0)
; #define PG8_LDB(dst, b, h) do { _Pragma("unroll") for (int n = 0; n < 2; ++n) _Pragma("unroll") for (int k = 0; k < 2; ++k) dst[n][k] = *(const PG8_LAS bf16x8*)(lds + PG8_SB(b, h) + boff + n * 2048 + k * 1024); } while (0)
; #define PG8_MMA(ai, bj, At, Bt) do { __builtin_amdgcn_s_setprio(1); _Pragma("unroll") for (int m = 0; m < 4; ++m) _Pragma("unroll") for (int n = 0; n < 2; ++n) _Pragma("unroll") for (int k = 0; k < 2; ++k) \
;         acc[ai][bj][m][n] = __builtin_amdgcn_mfma_f32_16x16x32_bf16(Bt[n][k], At[m][k], acc[ai][bj][m][n], 0, 0, 0); __builtin_amdgcn_s_setprio(0); } while (0)
; #define PG8_WAIT_V(n) asm volatile("s_waitcnt vmcnt(" #n ")" ::: "memory")
; #define PG8_WAIT_L(n) asm volatile("s_waitcnt lgkmcnt(" #n ")" ::: "memory")
; #define PG8_BAR __builtin_amdgcn_s_barrier()
; #define PG8_SCHED __builtin_amdgcn_sched_barrier(0)
; template <class Epi, class Sched, bool ALIGN_EPI = false, bool SP2 = false>
; __device__ __forceinline__ void gemm_phase(PG8_LAS unsigned char* lds, const Gemm g, const Sched& S, const Epi& E, int wid_in) {
;     ...
;             PG8_WAIT_V(8); PG8_WAIT_L(0); PG8_BAR; PG8_MMA(1, 0, At, B0); PG8_MMA(1, 1, At, B1); PG8_BAR; PG8_SCHED;
;             PG8_LDB(B0, 1, 0); PG8_LDB(B1, 1, 1); PG8_SCHED; PG8_LDA(At, 1, 0); PG8_STAGE(PG8_SA(0, 1), a2 + hstep, voffA);
;             PG8_WAIT_V(8); PG8_WAIT_L(0); PG8_BAR; PG8_MMA(0, 0, At, B0); PG8_MMA(0, 1, At, B1); PG8_BAR; PG8_SCHED;
	s_setprio 1
	v_mfma_f32_16x16x32_bf16 v[60:63], v[128:131], v[190:193], 0
	v_mfma_f32_16x16x32_bf16 v[56:59], v[158:161], v[190:193], 0
	v_mfma_f32_16x16x32_bf16 v[44:47], v[128:131], v[198:201], 0
	v_mfma_f32_16x16x32_bf16 v[40:43], v[158:161], v[198:201], 0
	v_mfma_f32_16x16x32_bf16 v[28:31], v[128:131], v[206:209], 0
	v_mfma_f32_16x16x32_bf16 v[24:27], v[158:161], v[206:209], 0
	v_mfma_f32_16x16x32_bf16 v[12:15], v[128:131], v[214:217], 0
	v_mfma_f32_16x16x32_bf16 v[8:11], v[158:161], v[214:217], 0
	v_mfma_f32_16x16x32_bf16 v[60:63], v[132:135], v[194:197], v[60:63]
	v_mfma_f32_16x16x32_bf16 v[56:59], v[162:165], v[194:197], v[56:59]
	v_mfma_f32_16x16x32_bf16 v[44:47], v[132:135], v[202:205], v[44:47]
	v_mfma_f32_16x16x32_bf16 v[40:43], v[162:165], v[202:205], v[40:43]
	v_mfma_f32_16x16x32_bf16 v[28:31], v[132:135], v[210:213], v[28:31]
	v_mfma_f32_16x16x32_bf16 v[24:27], v[162:165], v[210:213], v[24:27]
	v_mfma_f32_16x16x32_bf16 v[12:15], v[132:135], v[218:221], v[12:15]
	v_mfma_f32_16x16x32_bf16 v[8:11], v[162:165], v[218:221], v[8:11]
	v_mfma_f32_16x16x32_bf16 v[52:55], v[174:177], v[190:193], 0
	v_mfma_f32_16x16x32_bf16 v[48:51], v[182:185], v[190:193], 0
	v_mfma_f32_16x16x32_bf16 v[36:39], v[174:177], v[198:201], 0
	v_mfma_f32_16x16x32_bf16 v[32:35], v[182:185], v[198:201], 0
	v_mfma_f32_16x16x32_bf16 v[20:23], v[174:177], v[206:209], 0
	v_mfma_f32_16x16x32_bf16 v[16:19], v[182:185], v[206:209], 0
	v_mfma_f32_16x16x32_bf16 v[4:7], v[174:177], v[214:217], 0
	v_mfma_f32_16x16x32_bf16 v[0:3], v[182:185], v[214:217], 0
	v_mfma_f32_16x16x32_bf16 v[52:55], v[178:181], v[194:197], v[52:55]
	v_mfma_f32_16x16x32_bf16 v[48:51], v[186:189], v[194:197], v[48:51]
	v_mfma_f32_16x16x32_bf16 v[36:39], v[178:181], v[202:205], v[36:39]
	v_mfma_f32_16x16x32_bf16 v[32:35], v[186:189], v[202:205], v[32:35]
	v_mfma_f32_16x16x32_bf16 v[20:23], v[178:181], v[210:213], v[20:23]
	v_mfma_f32_16x16x32_bf16 v[16:19], v[186:189], v[210:213], v[16:19]
	v_mfma_f32_16x16x32_bf16 v[4:7], v[178:181], v[218:221], v[4:7]
	v_mfma_f32_16x16x32_bf16 v[0:3], v[186:189], v[218:221], v[0:3]
	s_setprio 0
	s_barrier
	s_add_i32 s95, 0, 0x18000
	v_add_u32_e32 v144, s95, v169
	s_add_i32 vcc_lo, 0, 0x1c000
	ds_read_b128 v[128:131], v144
	ds_read_b128 v[132:135], v144 offset:1024
	ds_read_b128 v[158:161], v144 offset:2048
	ds_read_b128 v[162:165], v144 offset:3072
	v_add_u32_e32 v144, vcc_lo, v169
	ds_read_b128 v[174:177], v144
	ds_read_b128 v[178:181], v144 offset:1024
	ds_read_b128 v[182:185], v144 offset:2048
	ds_read_b128 v[186:189], v144 offset:3072
	s_add_u32 s90, s90, 0x40000
	s_addc_u32 s91, s91, 0
	s_mov_b32 m0, s61
	v_lshl_add_u64 v[228:229], s[90:91], 0, v[136:137]
	ds_read_b128 v[190:193], v173 offset:32768
	ds_read_b128 v[194:197], v173 offset:33792
	ds_read_b128 v[198:201], v173 offset:34816
	ds_read_b128 v[202:205], v173 offset:35840
	ds_read_b128 v[206:209], v173 offset:36864
	ds_read_b128 v[210:213], v173 offset:37888
	ds_read_b128 v[214:217], v173 offset:38912
	ds_read_b128 v[218:221], v173 offset:39936
	global_load_lds_dwordx4 v[228:229], off
	v_lshl_add_u64 v[228:229], s[90:91], 0, v[140:141]
	s_mov_b32 m0, s62
	s_nop 0
	global_load_lds_dwordx4 v[228:229], off
	s_waitcnt vmcnt(8)
	s_waitcnt lgkmcnt(0)
	s_barrier
	s_setprio 1
	v_mfma_f32_16x16x32_bf16 v[124:127], v[128:131], v[190:193], v[124:127]
	v_mfma_f32_16x16x32_bf16 v[120:123], v[158:161], v[190:193], v[120:123]
	v_mfma_f32_16x16x32_bf16 v[108:111], v[128:131], v[198:201], v[108:111]
	v_mfma_f32_16x16x32_bf16 v[104:107], v[158:161], v[198:201], v[104:107]
	v_mfma_f32_16x16x32_bf16 v[92:95], v[128:131], v[206:209], v[92:95]
	v_mfma_f32_16x16x32_bf16 v[88:91], v[158:161], v[206:209], v[88:91]
	v_mfma_f32_16x16x32_bf16 v[76:79], v[128:131], v[214:217], v[76:79]
	v_mfma_f32_16x16x32_bf16 v[72:75], v[158:161], v[214:217], v[72:75]
	v_mfma_f32_16x16x32_bf16 v[124:127], v[132:135], v[194:197], v[124:127]
	v_mfma_f32_16x16x32_bf16 v[120:123], v[162:165], v[194:197], v[120:123]
	v_mfma_f32_16x16x32_bf16 v[108:111], v[132:135], v[202:205], v[108:111]
	v_mfma_f32_16x16x32_bf16 v[104:107], v[162:165], v[202:205], v[104:107]
	v_mfma_f32_16x16x32_bf16 v[92:95], v[132:135], v[210:213], v[92:95]
	v_mfma_f32_16x16x32_bf16 v[88:91], v[162:165], v[210:213], v[88:91]
	v_mfma_f32_16x16x32_bf16 v[76:79], v[132:135], v[218:221], v[76:79]
	v_mfma_f32_16x16x32_bf16 v[72:75], v[162:165], v[218:221], v[72:75]
	v_mfma_f32_16x16x32_bf16 v[116:119], v[174:177], v[190:193], v[116:119]
	v_mfma_f32_16x16x32_bf16 v[112:115], v[182:185], v[190:193], v[112:115]
	v_mfma_f32_16x16x32_bf16 v[100:103], v[174:177], v[198:201], v[100:103]
	v_mfma_f32_16x16x32_bf16 v[96:99], v[182:185], v[198:201], v[96:99]
	v_mfma_f32_16x16x32_bf16 v[84:87], v[174:177], v[206:209], v[84:87]
	v_mfma_f32_16x16x32_bf16 v[80:83], v[182:185], v[206:209], v[80:83]
	v_mfma_f32_16x16x32_bf16 v[68:71], v[174:177], v[214:217], v[68:71]
	v_mfma_f32_16x16x32_bf16 v[64:67], v[182:185], v[214:217], v[64:67]
	v_mfma_f32_16x16x32_bf16 v[116:119], v[178:181], v[194:197], v[116:119]
	v_mfma_f32_16x16x32_bf16 v[112:115], v[186:189], v[194:197], v[112:115]
	v_mfma_f32_16x16x32_bf16 v[100:103], v[178:181], v[202:205], v[100:103]
	v_mfma_f32_16x16x32_bf16 v[96:99], v[186:189], v[202:205], v[96:99]
	v_mfma_f32_16x16x32_bf16 v[84:87], v[178:181], v[210:213], v[84:87]
	v_mfma_f32_16x16x32_bf16 v[80:83], v[186:189], v[210:213], v[80:83]
	v_mfma_f32_16x16x32_bf16 v[68:71], v[178:181], v[218:221], v[68:71]
	v_mfma_f32_16x16x32_bf16 v[64:67], v[186:189], v[218:221], v[64:67]
	s_setprio 0
	s_barrier
; #define PG8_STAGE(bufoff, gbase, voff) do { _Pragma("unroll") for (int _i = 0; _i < 2; ++_i) \
;         __builtin_amdgcn_global_load_lds((const unsigned*)((const char*)(gbase) + (voff)[_i]), (PG8_LAS unsigned*)(lds + (bufoff) + ldsw + _i * 8192), 16, 0, 0); } while (0)
; #define PG8_LDA(dst, b, h) do { _Pragma("unroll") for (int m = 0; m < 4; ++m) _Pragma("unroll") for (int k = 0; k < 2; ++k) dst[m][k] = *(const PG8_LAS bf16x8*)(lds + PG8_SA(b, h) + aoff + m * 2048 + k * 1024); } while (0)
; #define PG8_MMA(ai, bj, At, Bt) do { __builtin_amdgcn_s_setprio(1); _Pragma("unroll") for (int m = 0; m < 4; ++m) _Pragma("unroll") for (int n = 0; n < 2; ++n) _Pragma("unroll") for (int k = 0; k < 2; ++k) \
;         acc[ai][bj][m][n] = __builtin_amdgcn_mfma_f32_16x16x32_bf16(Bt[n][k], At[m][k], acc[ai][bj][m][n], 0, 0, 0); __builtin_amdgcn_s_setprio(0); } while (0)
; #define PG8_WAIT_V(n) asm volatile("s_waitcnt vmcnt(" #n ")" ::: "memory")
; #define PG8_WAIT_L(n) asm volatile("s_waitcnt lgkmcnt(" #n ")" ::: "memory")
; #define PG8_BAR __builtin_amdgcn_s_barrier()
; #define PG8_SCHED __builtin_amdgcn_sched_barrier(0)
; template <class Epi, class Sched, bool ALIGN_EPI = false, bool SP2 = false>
; __device__ __forceinline__ void gemm_phase(PG8_LAS unsigned char* lds, const Gemm g, const Sched& S, const Epi& E, int wid_in) {
;     ...
;         for (int t = 0; t < nt; t += 2) {
;     ...
;             PG8_LDA(At, 1, 1); PG8_STAGE(PG8_SB(1, 0), b3, voffB); PG8_STAGE(PG8_SB(1, 1), b3 + hstep, voffB); PG8_STAGE(PG8_SA(1, 0), a3, voffA);
;             PG8_WAIT_V(8); PG8_WAIT_L(0); PG8_BAR; PG8_MMA(1, 0, At, B0); PG8_MMA(1, 1, At, B1); PG8_BAR; PG8_SCHED;
	s_add_i32 s90, s95, s12
	v_lshl_add_u64 v[166:167], v[166:167], 0, s[74:75]
	s_mov_b32 m0, s90
	ds_read_b128 v[190:193], v173 offset:49152
	ds_read_b128 v[194:197], v173 offset:50176
	ds_read_b128 v[198:201], v173 offset:51200
	ds_read_b128 v[202:205], v173 offset:52224
	ds_read_b128 v[206:209], v173 offset:53248
	ds_read_b128 v[210:213], v173 offset:54272
	ds_read_b128 v[214:217], v173 offset:55296
	ds_read_b128 v[218:221], v173 offset:56320
	global_load_lds_dwordx4 v[166:167], off
	s_add_i32 m0, s90, 0x2000
	s_add_u32 s88, s88, 0x40080
	v_lshl_add_u64 v[166:167], v[222:223], 0, s[74:75]
	s_addc_u32 s89, s89, 0
	s_add_i32 s90, vcc_lo, s12
	global_load_lds_dwordx4 v[166:167], off
	v_lshl_add_u64 v[166:167], s[88:89], 0, v[138:139]
	s_mov_b32 m0, s90
	s_nop 0
	global_load_lds_dwordx4 v[166:167], off
	v_lshl_add_u64 v[166:167], s[88:89], 0, v[142:143]
	s_add_i32 m0, s90, 0x2000
	s_nop 0
	global_load_lds_dwordx4 v[166:167], off
	v_lshl_add_u64 v[166:167], v[224:225], 0, s[74:75]
	s_mov_b32 m0, s64
	s_nop 0
	global_load_lds_dwordx4 v[166:167], off
	v_lshl_add_u64 v[166:167], v[226:227], 0, s[74:75]
	s_mov_b32 m0, s65
	s_nop 0
	global_load_lds_dwordx4 v[166:167], off
	s_waitcnt vmcnt(8)
	s_waitcnt lgkmcnt(0)
	s_barrier
	s_setprio 1
	v_mfma_f32_16x16x32_bf16 v[60:63], v[128:131], v[190:193], v[60:63]
	v_mfma_f32_16x16x32_bf16 v[56:59], v[158:161], v[190:193], v[56:59]
	v_mfma_f32_16x16x32_bf16 v[44:47], v[128:131], v[198:201], v[44:47]
	v_mfma_f32_16x16x32_bf16 v[40:43], v[158:161], v[198:201], v[40:43]
	v_mfma_f32_16x16x32_bf16 v[28:31], v[128:131], v[206:209], v[28:31]
	v_mfma_f32_16x16x32_bf16 v[24:27], v[158:161], v[206:209], v[24:27]
	v_mfma_f32_16x16x32_bf16 v[12:15], v[128:131], v[214:217], v[12:15]
	v_mfma_f32_16x16x32_bf16 v[8:11], v[158:161], v[214:217], v[8:11]
	v_mfma_f32_16x16x32_bf16 v[60:63], v[132:135], v[194:197], v[60:63]
	v_mfma_f32_16x16x32_bf16 v[56:59], v[162:165], v[194:197], v[56:59]
	v_mfma_f32_16x16x32_bf16 v[44:47], v[132:135], v[202:205], v[44:47]
	v_mfma_f32_16x16x32_bf16 v[40:43], v[162:165], v[202:205], v[40:43]
	v_mfma_f32_16x16x32_bf16 v[28:31], v[132:135], v[210:213], v[28:31]
	v_mfma_f32_16x16x32_bf16 v[24:27], v[162:165], v[210:213], v[24:27]
	v_mfma_f32_16x16x32_bf16 v[12:15], v[132:135], v[218:221], v[12:15]
	v_mfma_f32_16x16x32_bf16 v[8:11], v[162:165], v[218:221], v[8:11]
	v_mfma_f32_16x16x32_bf16 v[52:55], v[174:177], v[190:193], v[52:55]
	v_mfma_f32_16x16x32_bf16 v[48:51], v[182:185], v[190:193], v[48:51]
	v_mfma_f32_16x16x32_bf16 v[36:39], v[174:177], v[198:201], v[36:39]
	v_mfma_f32_16x16x32_bf16 v[32:35], v[182:185], v[198:201], v[32:35]
	v_mfma_f32_16x16x32_bf16 v[20:23], v[174:177], v[206:209], v[20:23]
	v_mfma_f32_16x16x32_bf16 v[16:19], v[182:185], v[206:209], v[16:19]
	v_mfma_f32_16x16x32_bf16 v[4:7], v[174:177], v[214:217], v[4:7]
	v_mfma_f32_16x16x32_bf16 v[0:3], v[182:185], v[214:217], v[0:3]
	v_mfma_f32_16x16x32_bf16 v[52:55], v[178:181], v[194:197], v[52:55]
	v_mfma_f32_16x16x32_bf16 v[48:51], v[186:189], v[194:197], v[48:51]
	v_mfma_f32_16x16x32_bf16 v[36:39], v[178:181], v[202:205], v[36:39]
	v_mfma_f32_16x16x32_bf16 v[32:35], v[186:189], v[202:205], v[32:35]
	v_mfma_f32_16x16x32_bf16 v[20:23], v[178:181], v[210:213], v[20:23]
	v_mfma_f32_16x16x32_bf16 v[16:19], v[186:189], v[210:213], v[16:19]
	v_mfma_f32_16x16x32_bf16 v[4:7], v[178:181], v[218:221], v[4:7]
	v_mfma_f32_16x16x32_bf16 v[0:3], v[186:189], v[218:221], v[0:3]
	s_setprio 0
	s_barrier
	s_add_i32 s94, s94, 2
	s_add_u32 s68, s68, 0x100
	s_addc_u32 s69, s69, 0
	s_add_u32 s92, s92, 0x100
	s_addc_u32 s93, s93, 0
	s_cmp_gt_u32 s94, 13
	.p2align	6

; #define PG8_STAGE(bufoff, gbase, voff) do { _Pragma("unroll") for (int _i = 0; _i < 2; ++_i) \
;         __builtin_amdgcn_global_load_lds((const unsigned*)((const char*)(gbase) + (voff)[_i]), (PG8_LAS unsigned*)(lds + (bufoff) + ldsw + _i * 8192), 16, 0, 0); } while (0)
; #define PG8_WAIT_V(n) asm volatile("s_waitcnt vmcnt(" #n ")" ::: "memory")
; #define PG8_BAR __builtin_amdgcn_s_barrier()
; template <int ROT, class Epi0, class Epi1, class Late, class Post0>
; __device__ __forceinline__ void gemm_phase_pair(PG8_LAS unsigned char* lds, const Gemm g0, const Gemm g1, const Unit u, const Epi0& E0, const Epi1& E1, int wid_in, const Late& late, const Post0& post0) {
;     ...
;     f32x4 acc[2][2][4][2];
; #pragma unroll
;     for (int a = 0; a < 2; ++a)
; #pragma unroll
;         for (int b = 0; b < 2; ++b)
; #pragma unroll
;             for (int m = 0; m < 4; ++m)
; #pragma unroll
;                 for (int n = 0; n < 2; ++n) acc[a][b][m][n] = (f32x4){0.f, 0.f, 0.f, 0.f};
;     bf16x8 At[4][2], B0[2][2], B1[2][2];
;     const char* cA = (const char*)g0.A + (size_t)u.pm * 2 * hs0; const char* cB = (const char*)g0.Bt + (size_t)u.pn * 2 * hs0;
;     const char* nA = (const char*)g1.A + (size_t)u.pm * 2 * hs1; const char* nB = (const char*)g1.Bt + (size_t)u.pn * 2 * hs1;
;     ...
;     PG8_STAGE(PG8_SB(0, 0), cB + PG8_KT(0), vB0); PG8_STAGE(PG8_SB(0, 1), cB + hs0 + PG8_KT(0), vB0); PG8_STAGE(PG8_SA(0, 0), cA + PG8_KT(0), vA0); PG8_STAGE(PG8_SA(0, 1), cA + hs0 + PG8_KT(0), vA0);
;     if (wr == 1) PG8_BAR;
;     PG8_WAIT_V(2); PG8_BAR;
;     PG8_STAGE(PG8_SB(1, 0), cB + PG8_KT(1), vB0); PG8_STAGE(PG8_SA(1, 0), cA + PG8_KT(1), vA0); PG8_STAGE(PG8_SB(1, 1), cB + hs0 + PG8_KT(1), vB0);
;     PG8_WAIT_V(6); PG8_BAR;
.LBB0_846:
	v_readlane_b32 s7, v252, 5
	s_lshl_b32 s7, s7, 5
	s_and_b32 s52, s7, 0x60
	s_lshl_b32 s12, s6, 6
	v_ashrrev_i32_e32 v1, 6, v143
	s_lshr_b32 s7, s52, 3
	s_lshl_b32 s6, s6, 13
	v_lshl_add_u32 v12, v1, 10, s6
	v_add_lshl_u32 v1, v1, s7, 10
	s_mov_b64 s[6:7], 0x880
	s_add_i32 m0, s40, 0x18000
	v_lshl_add_u64 v[2:3], v[2:3], 0, s[6:7]
	s_waitcnt vmcnt(2)
	s_barrier
	global_load_lds_dwordx4 v[2:3], off
	v_lshl_add_u64 v[2:3], v[4:5], 0, s[6:7]
	s_add_i32 m0, s40, 0x1a000
	s_add_i32 s13, s40, 0x8000
	s_add_i32 s33, s40, 0xa000
	global_load_lds_dwordx4 v[2:3], off
	v_lshl_add_u64 v[2:3], v[6:7], 0, s[6:7]
	s_mov_b32 m0, s13
	s_add_u32 s4, s4, 0x80880
	global_load_lds_dwordx4 v[2:3], off
	v_lshl_add_u64 v[2:3], v[8:9], 0, s[6:7]
	s_mov_b32 m0, s33
	s_addc_u32 s5, s5, 0
	global_load_lds_dwordx4 v[2:3], off
	s_add_i32 m0, s40, 0x1c000
	v_lshl_add_u64 v[2:3], s[4:5], 0, v[132:133]
	global_load_lds_dwordx4 v[2:3], off
	v_lshl_add_u64 v[2:3], s[4:5], 0, v[130:131]
	s_add_i32 m0, s40, 0x1e000
	v_and_b32_e32 v136, 15, v143
	global_load_lds_dwordx4 v[2:3], off
	v_and_b32_e32 v10, 48, v143
	v_lshlrev_b32_e32 v11, 2, v143
	v_lshl_or_b32 v10, v136, 6, v10
	v_and_b32_e32 v11, 32, v11
	v_bitop3_b32 v1, v10, v1, v11 bitop3:0xde
	s_waitcnt vmcnt(6)
	s_add_i32 s49, 0, 0x10000
	s_add_i32 s48, 0, 0x14000
	s_add_i32 s44, 0, 0x18000
	s_add_i32 s43, 0, 0x1c000
	v_bitop3_b32 v10, v10, v12, v11 bitop3:0xde
	v_add_u32_e32 v141, s49, v1
	v_add_u32_e32 v140, s48, v1
	s_add_i32 s49, s49, s36
	s_add_i32 s48, s48, s36
	v_add_u32_e32 v139, s44, v1
	v_add_u32_e32 v138, s43, v1
	s_add_i32 s44, s44, s36
	s_add_i32 s43, s43, s36
	v_or_b32_e32 v142, s12, v136
	v_add_u32_e32 v137, 0, v10
	s_mov_b32 s53, -2
	s_mov_b64 s[4:5], 0x8c80880
	s_add_i32 s51, s40, 0xc000
	s_add_i32 s50, s40, 0xe000
	s_mov_b64 s[6:7], 0xd00900
	s_add_i32 s47, s49, 0x2000
	s_mov_b64 s[10:11], 0xd80900
	s_add_i32 s46, s48, 0x2000
	s_mov_b64 s[24:25], 0x8c00900
	s_mov_b64 s[26:27], 0x8c80900
	s_mov_b64 s[28:29], 0xd00980
	s_add_i32 s42, s44, 0x2000
	s_mov_b64 s[30:31], 0xd80980
	s_add_i32 s41, s43, 0x2000
	s_mov_b64 s[36:37], 0x8c00980
	s_mov_b64 s[38:39], s[96:97]
	v_mov_b32_e32 v134, v130
	v_mov_b32_e32 v130, v0
	v_mov_b32_e32 v0, v131
	v_mov_b32_e32 v1, v131
	v_mov_b32_e32 v2, v131
	v_mov_b32_e32 v3, v131
	v_mov_b32_e32 v4, v131
	v_mov_b32_e32 v5, v131
	v_mov_b32_e32 v6, v131
	v_mov_b32_e32 v7, v131
	v_mov_b32_e32 v8, v131
	v_mov_b32_e32 v9, v131
	v_mov_b32_e32 v10, v131
	v_mov_b32_e32 v11, v131
	v_mov_b32_e32 v12, v131
	v_mov_b32_e32 v13, v131
	v_mov_b32_e32 v14, v131
	v_mov_b32_e32 v15, v131
	v_mov_b32_e32 v16, v131
	v_mov_b32_e32 v17, v131
	v_mov_b32_e32 v18, v131
	v_mov_b32_e32 v19, v131
	v_mov_b32_e32 v20, v131
	v_mov_b32_e32 v21, v131
	v_mov_b32_e32 v22, v131
	v_mov_b32_e32 v23, v131
	v_mov_b32_e32 v24, v131
	v_mov_b32_e32 v25, v131
	v_mov_b32_e32 v26, v131
	v_mov_b32_e32 v27, v131
	v_mov_b32_e32 v28, v131
	v_mov_b32_e32 v29, v131
	v_mov_b32_e32 v30, v131
	v_mov_b32_e32 v31, v131
	v_mov_b32_e32 v32, v131
	v_mov_b32_e32 v33, v131
	v_mov_b32_e32 v34, v131
	v_mov_b32_e32 v35, v131
	v_mov_b32_e32 v36, v131
	v_mov_b32_e32 v37, v131
	v_mov_b32_e32 v38, v131
	v_mov_b32_e32 v39, v131
	v_mov_b32_e32 v40, v131
	v_mov_b32_e32 v41, v131
	v_mov_b32_e32 v42, v131
	v_mov_b32_e32 v43, v131
	v_mov_b32_e32 v44, v131
	v_mov_b32_e32 v45, v131
	v_mov_b32_e32 v46, v131
	v_mov_b32_e32 v47, v131
	v_mov_b32_e32 v48, v131
	v_mov_b32_e32 v49, v131
	v_mov_b32_e32 v50, v131
	v_mov_b32_e32 v51, v131
	v_mov_b32_e32 v52, v131
	v_mov_b32_e32 v53, v131
	v_mov_b32_e32 v54, v131
	v_mov_b32_e32 v55, v131
	v_mov_b32_e32 v56, v131
	v_mov_b32_e32 v57, v131
	v_mov_b32_e32 v58, v131
	v_mov_b32_e32 v59, v131
	v_mov_b32_e32 v60, v131
	v_mov_b32_e32 v61, v131
	v_mov_b32_e32 v62, v131
	v_mov_b32_e32 v63, v131
	v_mov_b32_e32 v64, v131
	v_mov_b32_e32 v65, v131
	v_mov_b32_e32 v66, v131
	v_mov_b32_e32 v67, v131
	v_mov_b32_e32 v68, v131
	v_mov_b32_e32 v69, v131
	v_mov_b32_e32 v70, v131
	v_mov_b32_e32 v71, v131
	v_mov_b32_e32 v72, v131
	v_mov_b32_e32 v73, v131
	v_mov_b32_e32 v74, v131
	v_mov_b32_e32 v75, v131
	v_mov_b32_e32 v76, v131
	v_mov_b32_e32 v77, v131
	v_mov_b32_e32 v78, v131
	v_mov_b32_e32 v79, v131
	v_mov_b32_e32 v80, v131
	v_mov_b32_e32 v81, v131
	v_mov_b32_e32 v82, v131
	v_mov_b32_e32 v83, v131
	v_mov_b32_e32 v84, v131
	v_mov_b32_e32 v85, v131
	v_mov_b32_e32 v86, v131
	v_mov_b32_e32 v87, v131
	v_mov_b32_e32 v88, v131
	v_mov_b32_e32 v89, v131
	v_mov_b32_e32 v90, v131
	v_mov_b32_e32 v91, v131
	v_mov_b32_e32 v92, v131
	v_mov_b32_e32 v93, v131
	v_mov_b32_e32 v94, v131
	v_mov_b32_e32 v95, v131
	v_mov_b32_e32 v96, v131
	v_mov_b32_e32 v97, v131
	v_mov_b32_e32 v98, v131
	v_mov_b32_e32 v99, v131
	v_mov_b32_e32 v100, v131
	v_mov_b32_e32 v101, v131
	v_mov_b32_e32 v102, v131
	v_mov_b32_e32 v103, v131
	v_mov_b32_e32 v104, v131
	v_mov_b32_e32 v105, v131
	v_mov_b32_e32 v106, v131
	v_mov_b32_e32 v107, v131
	v_mov_b32_e32 v108, v131
	v_mov_b32_e32 v109, v131
	v_mov_b32_e32 v110, v131
	v_mov_b32_e32 v111, v131
	v_mov_b32_e32 v112, v131
	v_mov_b32_e32 v113, v131
	v_mov_b32_e32 v114, v131
	v_mov_b32_e32 v115, v131
	v_mov_b32_e32 v116, v131
	v_mov_b32_e32 v117, v131
	v_mov_b32_e32 v118, v131
	v_mov_b32_e32 v119, v131
	v_mov_b32_e32 v120, v131
	v_mov_b32_e32 v121, v131
	v_mov_b32_e32 v122, v131
	v_mov_b32_e32 v123, v131
	v_mov_b32_e32 v124, v131
	v_mov_b32_e32 v125, v131
	v_mov_b32_e32 v126, v131
	v_mov_b32_e32 v127, v131
	s_barrier
	s_mov_b32 s98, 0
	.p2align	6

.Llate_w0b:
	s_waitcnt lgkmcnt(0)
	s_barrier
	s_setprio 1
	v_mfma_f32_16x16x32_bf16 v[124:127], v[144:147], v[176:179], v[124:127]
	v_mfma_f32_16x16x32_bf16 v[120:123], v[152:155], v[176:179], v[120:123]
	v_mfma_f32_16x16x32_bf16 v[116:119], v[144:147], v[184:187], v[116:119]
	v_mfma_f32_16x16x32_bf16 v[112:115], v[152:155], v[184:187], v[112:115]
	v_mfma_f32_16x16x32_bf16 v[108:111], v[144:147], v[192:195], v[108:111]
	v_mfma_f32_16x16x32_bf16 v[104:107], v[152:155], v[192:195], v[104:107]
	v_mfma_f32_16x16x32_bf16 v[100:103], v[144:147], v[200:203], v[100:103]
	v_mfma_f32_16x16x32_bf16 v[96:99], v[152:155], v[200:203], v[96:99]
	v_mfma_f32_16x16x32_bf16 v[124:127], v[148:151], v[180:183], v[124:127]
	v_mfma_f32_16x16x32_bf16 v[120:123], v[156:159], v[180:183], v[120:123]
	v_mfma_f32_16x16x32_bf16 v[116:119], v[148:151], v[188:191], v[116:119]
	v_mfma_f32_16x16x32_bf16 v[112:115], v[156:159], v[188:191], v[112:115]
	v_mfma_f32_16x16x32_bf16 v[108:111], v[148:151], v[196:199], v[108:111]
	v_mfma_f32_16x16x32_bf16 v[104:107], v[156:159], v[196:199], v[104:107]
	v_mfma_f32_16x16x32_bf16 v[100:103], v[148:151], v[204:207], v[100:103]
	v_mfma_f32_16x16x32_bf16 v[96:99], v[156:159], v[204:207], v[96:99]
	v_mfma_f32_16x16x32_bf16 v[92:95], v[160:163], v[176:179], v[92:95]
	v_mfma_f32_16x16x32_bf16 v[88:91], v[168:171], v[176:179], v[88:91]
	v_mfma_f32_16x16x32_bf16 v[84:87], v[160:163], v[184:187], v[84:87]
	v_mfma_f32_16x16x32_bf16 v[80:83], v[168:171], v[184:187], v[80:83]
	v_mfma_f32_16x16x32_bf16 v[76:79], v[160:163], v[192:195], v[76:79]
	v_mfma_f32_16x16x32_bf16 v[72:75], v[168:171], v[192:195], v[72:75]
	v_mfma_f32_16x16x32_bf16 v[68:71], v[160:163], v[200:203], v[68:71]
	v_mfma_f32_16x16x32_bf16 v[64:67], v[168:171], v[200:203], v[64:67]
	v_mfma_f32_16x16x32_bf16 v[92:95], v[164:167], v[180:183], v[92:95]
	v_mfma_f32_16x16x32_bf16 v[88:91], v[172:175], v[180:183], v[88:91]
	v_mfma_f32_16x16x32_bf16 v[84:87], v[164:167], v[188:191], v[84:87]
	v_mfma_f32_16x16x32_bf16 v[80:83], v[172:175], v[188:191], v[80:83]
	v_mfma_f32_16x16x32_bf16 v[76:79], v[164:167], v[196:199], v[76:79]
	v_mfma_f32_16x16x32_bf16 v[72:75], v[172:175], v[196:199], v[72:75]
	v_mfma_f32_16x16x32_bf16 v[68:71], v[164:167], v[204:207], v[68:71]
	v_mfma_f32_16x16x32_bf16 v[64:67], v[172:175], v[204:207], v[64:67]
	s_setprio 0
	s_barrier
	s_add_u32 s62, s38, s20
	v_mov_b32_e32 v133, v131
	s_addc_u32 s63, s39, s21
	v_lshl_add_u64 v[212:213], s[62:63], 0, v[132:133]
	s_mov_b32 m0, s49
	v_lshl_add_u64 v[214:215], v[212:213], 0, s[6:7]
	v_mov_b32_e32 v135, v131
	ds_read_b128 v[176:179], v137 offset:16384
	ds_read_b128 v[180:183], v137 offset:17408
	ds_read_b128 v[184:187], v137 offset:18432
	ds_read_b128 v[188:191], v137 offset:19456
	ds_read_b128 v[192:195], v137 offset:20480
	ds_read_b128 v[196:199], v137 offset:21504
	ds_read_b128 v[200:203], v137 offset:22528
	ds_read_b128 v[204:207], v137 offset:23552
	global_load_lds_dwordx4 v[214:215], off
	v_lshl_add_u64 v[214:215], s[62:63], 0, v[134:135]
	v_lshl_add_u64 v[216:217], v[214:215], 0, s[6:7]
	s_mov_b32 m0, s47
	s_nop 0
	global_load_lds_dwordx4 v[216:217], off
	v_lshl_add_u64 v[216:217], v[212:213], 0, s[10:11]
	s_mov_b32 m0, s48
	s_nop 0
	global_load_lds_dwordx4 v[216:217], off
	v_lshl_add_u64 v[216:217], v[214:215], 0, s[10:11]
	s_mov_b32 m0, s46
	s_nop 0
	global_load_lds_dwordx4 v[216:217], off
	v_lshl_add_u64 v[216:217], v[208:209], 0, s[24:25]
	s_mov_b32 m0, s40
	s_nop 0
	global_load_lds_dwordx4 v[216:217], off
	v_lshl_add_u64 v[216:217], v[210:211], 0, s[24:25]
	s_mov_b32 m0, s45
	s_nop 0
	global_load_lds_dwordx4 v[216:217], off
	s_cmp_eq_u32 s98, 1
	s_cbranch_scc1 .Llate_w1a
	s_waitcnt vmcnt(8)
	s_branch .Llate_w1b

.Llate_w1b:
	s_waitcnt lgkmcnt(0)
	s_barrier
	s_setprio 1
	v_mfma_f32_16x16x32_bf16 v[60:63], v[144:147], v[176:179], v[60:63]
	v_mfma_f32_16x16x32_bf16 v[56:59], v[152:155], v[176:179], v[56:59]
	v_mfma_f32_16x16x32_bf16 v[52:55], v[144:147], v[184:187], v[52:55]
	v_mfma_f32_16x16x32_bf16 v[48:51], v[152:155], v[184:187], v[48:51]
	v_mfma_f32_16x16x32_bf16 v[44:47], v[144:147], v[192:195], v[44:47]
	v_mfma_f32_16x16x32_bf16 v[40:43], v[152:155], v[192:195], v[40:43]
	v_mfma_f32_16x16x32_bf16 v[36:39], v[144:147], v[200:203], v[36:39]
	v_mfma_f32_16x16x32_bf16 v[32:35], v[152:155], v[200:203], v[32:35]
	v_mfma_f32_16x16x32_bf16 v[60:63], v[148:151], v[180:183], v[60:63]
	v_mfma_f32_16x16x32_bf16 v[56:59], v[156:159], v[180:183], v[56:59]
	v_mfma_f32_16x16x32_bf16 v[52:55], v[148:151], v[188:191], v[52:55]
	v_mfma_f32_16x16x32_bf16 v[48:51], v[156:159], v[188:191], v[48:51]
	v_mfma_f32_16x16x32_bf16 v[44:47], v[148:151], v[196:199], v[44:47]
	v_mfma_f32_16x16x32_bf16 v[40:43], v[156:159], v[196:199], v[40:43]
	v_mfma_f32_16x16x32_bf16 v[36:39], v[148:151], v[204:207], v[36:39]
	v_mfma_f32_16x16x32_bf16 v[32:35], v[156:159], v[204:207], v[32:35]
	v_mfma_f32_16x16x32_bf16 v[28:31], v[160:163], v[176:179], v[28:31]
	v_mfma_f32_16x16x32_bf16 v[24:27], v[168:171], v[176:179], v[24:27]
	v_mfma_f32_16x16x32_bf16 v[20:23], v[160:163], v[184:187], v[20:23]
	v_mfma_f32_16x16x32_bf16 v[16:19], v[168:171], v[184:187], v[16:19]
	v_mfma_f32_16x16x32_bf16 v[12:15], v[160:163], v[192:195], v[12:15]
	v_mfma_f32_16x16x32_bf16 v[8:11], v[168:171], v[192:195], v[8:11]
	v_mfma_f32_16x16x32_bf16 v[4:7], v[160:163], v[200:203], v[4:7]
	v_mfma_f32_16x16x32_bf16 v[0:3], v[168:171], v[200:203], v[0:3]
	v_mfma_f32_16x16x32_bf16 v[28:31], v[164:167], v[180:183], v[28:31]
	v_mfma_f32_16x16x32_bf16 v[24:27], v[172:175], v[180:183], v[24:27]
	v_mfma_f32_16x16x32_bf16 v[20:23], v[164:167], v[188:191], v[20:23]
	v_mfma_f32_16x16x32_bf16 v[16:19], v[172:175], v[188:191], v[16:19]
	v_mfma_f32_16x16x32_bf16 v[12:15], v[164:167], v[196:199], v[12:15]
	v_mfma_f32_16x16x32_bf16 v[8:11], v[172:175], v[196:199], v[8:11]
	v_mfma_f32_16x16x32_bf16 v[4:7], v[164:167], v[204:207], v[4:7]
	v_mfma_f32_16x16x32_bf16 v[0:3], v[172:175], v[204:207], v[0:3]
	s_setprio 0
	s_barrier
	ds_read_b128 v[144:147], v139
	ds_read_b128 v[148:151], v139 offset:1024
	ds_read_b128 v[152:155], v139 offset:2048
	ds_read_b128 v[156:159], v139 offset:3072
	ds_read_b128 v[160:163], v138
	ds_read_b128 v[164:167], v138 offset:1024
	ds_read_b128 v[168:171], v138 offset:2048
	ds_read_b128 v[172:175], v138 offset:3072
	s_mov_b32 m0, s34
	v_lshl_add_u64 v[216:217], v[208:209], 0, s[26:27]
	ds_read_b128 v[176:179], v137 offset:32768
	ds_read_b128 v[180:183], v137 offset:33792
	ds_read_b128 v[184:187], v137 offset:34816
	ds_read_b128 v[188:191], v137 offset:35840
	ds_read_b128 v[192:195], v137 offset:36864
	ds_read_b128 v[196:199], v137 offset:37888
	ds_read_b128 v[200:203], v137 offset:38912
	ds_read_b128 v[204:207], v137 offset:39936
	global_load_lds_dwordx4 v[216:217], off
	v_lshl_add_u64 v[216:217], v[210:211], 0, s[26:27]
	s_mov_b32 m0, s35
	s_nop 0
	global_load_lds_dwordx4 v[216:217], off
	s_waitcnt vmcnt(8)
	s_waitcnt lgkmcnt(0)
	s_barrier
	s_setprio 1
	v_mfma_f32_16x16x32_bf16 v[124:127], v[144:147], v[176:179], v[124:127]
	v_mfma_f32_16x16x32_bf16 v[120:123], v[152:155], v[176:179], v[120:123]
	v_mfma_f32_16x16x32_bf16 v[116:119], v[144:147], v[184:187], v[116:119]
	v_mfma_f32_16x16x32_bf16 v[112:115], v[152:155], v[184:187], v[112:115]
	v_mfma_f32_16x16x32_bf16 v[108:111], v[144:147], v[192:195], v[108:111]
	v_mfma_f32_16x16x32_bf16 v[104:107], v[152:155], v[192:195], v[104:107]
	v_mfma_f32_16x16x32_bf16 v[100:103], v[144:147], v[200:203], v[100:103]
	v_mfma_f32_16x16x32_bf16 v[96:99], v[152:155], v[200:203], v[96:99]
	v_mfma_f32_16x16x32_bf16 v[124:127], v[148:151], v[180:183], v[124:127]
	v_mfma_f32_16x16x32_bf16 v[120:123], v[156:159], v[180:183], v[120:123]
	v_mfma_f32_16x16x32_bf16 v[116:119], v[148:151], v[188:191], v[116:119]
	v_mfma_f32_16x16x32_bf16 v[112:115], v[156:159], v[188:191], v[112:115]
	v_mfma_f32_16x16x32_bf16 v[108:111], v[148:151], v[196:199], v[108:111]
	v_mfma_f32_16x16x32_bf16 v[104:107], v[156:159], v[196:199], v[104:107]
	v_mfma_f32_16x16x32_bf16 v[100:103], v[148:151], v[204:207], v[100:103]
	v_mfma_f32_16x16x32_bf16 v[96:99], v[156:159], v[204:207], v[96:99]
	v_mfma_f32_16x16x32_bf16 v[92:95], v[160:163], v[176:179], v[92:95]
	v_mfma_f32_16x16x32_bf16 v[88:91], v[168:171], v[176:179], v[88:91]
	v_mfma_f32_16x16x32_bf16 v[84:87], v[160:163], v[184:187], v[84:87]
	v_mfma_f32_16x16x32_bf16 v[80:83], v[168:171], v[184:187], v[80:83]
	v_mfma_f32_16x16x32_bf16 v[76:79], v[160:163], v[192:195], v[76:79]
	v_mfma_f32_16x16x32_bf16 v[72:75], v[168:171], v[192:195], v[72:75]
	v_mfma_f32_16x16x32_bf16 v[68:71], v[160:163], v[200:203], v[68:71]
	v_mfma_f32_16x16x32_bf16 v[64:67], v[168:171], v[200:203], v[64:67]
	v_mfma_f32_16x16x32_bf16 v[92:95], v[164:167], v[180:183], v[92:95]
	v_mfma_f32_16x16x32_bf16 v[88:91], v[172:175], v[180:183], v[88:91]
	v_mfma_f32_16x16x32_bf16 v[84:87], v[164:167], v[188:191], v[84:87]
	v_mfma_f32_16x16x32_bf16 v[80:83], v[172:175], v[188:191], v[80:83]
	v_mfma_f32_16x16x32_bf16 v[76:79], v[164:167], v[196:199], v[76:79]
	v_mfma_f32_16x16x32_bf16 v[72:75], v[172:175], v[196:199], v[72:75]
	v_mfma_f32_16x16x32_bf16 v[68:71], v[164:167], v[204:207], v[68:71]
	v_mfma_f32_16x16x32_bf16 v[64:67], v[172:175], v[204:207], v[64:67]
	s_setprio 0
	s_barrier
; #define PG8_BAR __builtin_amdgcn_s_barrier()
; template <int ROT, class Epi0, class Epi1, class Late, class Post0>
; __device__ __forceinline__ void gemm_phase_pair(PG8_LAS unsigned char* lds, const Gemm g0, const Gemm g1, const Unit u, const Epi0& E0, const Epi1& E1, int wid_in, const Late& late, const Post0& post0) {
;     ...
;     for (int t = 0; t < t_late; t += 2) {
;         const char* a1 = cA + PG8_KT(t + 1); const char* a2 = cA + PG8_KT(t + 2); const char* b2 = cB + PG8_KT(t + 2); const char* a3 = cA + PG8_KT(t + 3); const char* b3 = cB + PG8_KT(t + 3);
;         PG8_PAIR_ITER(a1 + hs0, vA0, a2, b2, a3, b3, vA0, vB0, hs0);
;     }
;     if (ROT != 0) {
;         if (wr == 0) PG8_BAR;
	s_mov_b32 m0, s44
	v_lshl_add_u64 v[216:217], v[212:213], 0, s[28:29]
	ds_read_b128 v[176:179], v137 offset:49152
	ds_read_b128 v[180:183], v137 offset:50176
	ds_read_b128 v[184:187], v137 offset:51200
	ds_read_b128 v[188:191], v137 offset:52224
	ds_read_b128 v[192:195], v137 offset:53248
	ds_read_b128 v[196:199], v137 offset:54272
	ds_read_b128 v[200:203], v137 offset:55296
	ds_read_b128 v[204:207], v137 offset:56320
	global_load_lds_dwordx4 v[216:217], off
	v_lshl_add_u64 v[216:217], v[214:215], 0, s[28:29]
	s_mov_b32 m0, s42
	v_lshl_add_u64 v[212:213], v[212:213], 0, s[30:31]
	global_load_lds_dwordx4 v[216:217], off
	s_mov_b32 m0, s43
	v_lshl_add_u64 v[208:209], v[208:209], 0, s[36:37]
	global_load_lds_dwordx4 v[212:213], off
	v_lshl_add_u64 v[212:213], v[214:215], 0, s[30:31]
	s_mov_b32 m0, s41
	s_nop 0
	global_load_lds_dwordx4 v[212:213], off
	s_mov_b32 m0, s13
	s_nop 0
	global_load_lds_dwordx4 v[208:209], off
	v_lshl_add_u64 v[208:209], v[210:211], 0, s[36:37]
	s_mov_b32 m0, s33
	s_nop 0
	global_load_lds_dwordx4 v[208:209], off
	s_waitcnt vmcnt(8)
	s_waitcnt lgkmcnt(0)
	s_barrier
	s_setprio 1
	v_mfma_f32_16x16x32_bf16 v[60:63], v[144:147], v[176:179], v[60:63]
	v_mfma_f32_16x16x32_bf16 v[56:59], v[152:155], v[176:179], v[56:59]
	v_mfma_f32_16x16x32_bf16 v[52:55], v[144:147], v[184:187], v[52:55]
	v_mfma_f32_16x16x32_bf16 v[48:51], v[152:155], v[184:187], v[48:51]
	v_mfma_f32_16x16x32_bf16 v[44:47], v[144:147], v[192:195], v[44:47]
	v_mfma_f32_16x16x32_bf16 v[40:43], v[152:155], v[192:195], v[40:43]
	v_mfma_f32_16x16x32_bf16 v[36:39], v[144:147], v[200:203], v[36:39]
	v_mfma_f32_16x16x32_bf16 v[32:35], v[152:155], v[200:203], v[32:35]
	v_mfma_f32_16x16x32_bf16 v[60:63], v[148:151], v[180:183], v[60:63]
	v_mfma_f32_16x16x32_bf16 v[56:59], v[156:159], v[180:183], v[56:59]
	v_mfma_f32_16x16x32_bf16 v[52:55], v[148:151], v[188:191], v[52:55]
	v_mfma_f32_16x16x32_bf16 v[48:51], v[156:159], v[188:191], v[48:51]
	v_mfma_f32_16x16x32_bf16 v[44:47], v[148:151], v[196:199], v[44:47]
	v_mfma_f32_16x16x32_bf16 v[40:43], v[156:159], v[196:199], v[40:43]
	v_mfma_f32_16x16x32_bf16 v[36:39], v[148:151], v[204:207], v[36:39]
	v_mfma_f32_16x16x32_bf16 v[32:35], v[156:159], v[204:207], v[32:35]
	v_mfma_f32_16x16x32_bf16 v[28:31], v[160:163], v[176:179], v[28:31]
	v_mfma_f32_16x16x32_bf16 v[24:27], v[168:171], v[176:179], v[24:27]
	v_mfma_f32_16x16x32_bf16 v[20:23], v[160:163], v[184:187], v[20:23]
	v_mfma_f32_16x16x32_bf16 v[16:19], v[168:171], v[184:187], v[16:19]
	v_mfma_f32_16x16x32_bf16 v[12:15], v[160:163], v[192:195], v[12:15]
	v_mfma_f32_16x16x32_bf16 v[8:11], v[168:171], v[192:195], v[8:11]
	v_mfma_f32_16x16x32_bf16 v[4:7], v[160:163], v[200:203], v[4:7]
	v_mfma_f32_16x16x32_bf16 v[0:3], v[168:171], v[200:203], v[0:3]
	v_mfma_f32_16x16x32_bf16 v[28:31], v[164:167], v[180:183], v[28:31]
	v_mfma_f32_16x16x32_bf16 v[24:27], v[172:175], v[180:183], v[24:27]
	v_mfma_f32_16x16x32_bf16 v[20:23], v[164:167], v[188:191], v[20:23]
	v_mfma_f32_16x16x32_bf16 v[16:19], v[172:175], v[188:191], v[16:19]
	v_mfma_f32_16x16x32_bf16 v[12:15], v[164:167], v[196:199], v[12:15]
	v_mfma_f32_16x16x32_bf16 v[8:11], v[172:175], v[196:199], v[8:11]
	v_mfma_f32_16x16x32_bf16 v[4:7], v[164:167], v[204:207], v[4:7]
	v_mfma_f32_16x16x32_bf16 v[0:3], v[172:175], v[204:207], v[0:3]
	s_setprio 0
	s_barrier
	s_add_i32 s53, s53, 2
	s_add_u32 s38, s38, 0x100
	s_addc_u32 s39, s39, 0
	s_cmp_gt_u32 s53, 11
	s_cbranch_scc0 .LBB0_847
	s_cmpk_lt_u32 s71, 0x100
	s_cselect_b64 s[4:5], -1, 0
	s_and_b64 vcc, exec, s[4:5]
	s_cbranch_vccz .LBB0_850
	s_barrier

; #define PG8_STAGE(bufoff, gbase, voff) do { _Pragma("unroll") for (int _i = 0; _i < 2; ++_i) \
;         __builtin_amdgcn_global_load_lds((const unsigned*)((const char*)(gbase) + (voff)[_i]), (PG8_LAS unsigned*)(lds + (bufoff) + ldsw + _i * 8192), 16, 0, 0); } while (0)
; #define PG8_LDA(dst, b, h) do { _Pragma("unroll") for (int m = 0; m < 4; ++m) _Pragma("unroll") for (int k = 0; k < 2; ++k) dst[m][k] = *(const PG8_LAS bf16x8*)(lds + PG8_SA(b, h) + aoff + m * 2048 + k * 1024); } while (0)
; #define PG8_LDB(dst, b, h) do { _Pragma("unroll") for (int n = 0; n < 2; ++n) _Pragma("unroll") for (int k = 0; k < 2; ++k) dst[n][k] = *(const PG8_LAS bf16x8*)(lds + PG8_SB(b, h) + boff + n * 2048 + k * 1024); } while (0)
; #define PG8_MMA(ai, bj, At, Bt) do { __builtin_amdgcn_s_setprio(1); _Pragma("unroll") for (int m = 0; m < 4; ++m) _Pragma("unroll") for (int n = 0; n < 2; ++n) _Pragma("unroll") for (int k = 0; k < 2; ++k) \
;         acc[ai][bj][m][n] = __builtin_amdgcn_mfma_f32_16x16x32_bf16(Bt[n][k], At[m][k], acc[ai][bj][m][n], 0, 0, 0); __builtin_amdgcn_s_setprio(0); } while (0)
; #define PG8_WAIT_V(n) asm volatile("s_waitcnt vmcnt(" #n ")" ::: "memory")
; #define PG8_WAIT_L(n) asm volatile("s_waitcnt lgkmcnt(" #n ")" ::: "memory")
; #define PG8_BAR __builtin_amdgcn_s_barrier()
; #define PG8_SCHED __builtin_amdgcn_sched_barrier(0)
; template <class Epi, class Sched, bool ALIGN_EPI = false, bool SP2 = false>
; __device__ __forceinline__ void gemm_phase(PG8_LAS unsigned char* lds, const Gemm g, const Sched& S, const Epi& E, int wid_in) {
;     ...
;             PG8_LDB(B0, 0, 0); PG8_LDB(B1, 0, 1); PG8_SCHED; PG8_LDA(At, 0, 0); PG8_STAGE(PG8_SA(1, 1), a1 + hstep, voffA);
;             PG8_WAIT_V(8); PG8_WAIT_L(0); PG8_BAR; PG8_MMA(0, 0, At, B0); PG8_MMA(0, 1, At, B1); PG8_BAR; PG8_SCHED;
;             PG8_LDA(At, 0, 1); PG8_STAGE(PG8_SB(0, 0), b2, voffB); PG8_STAGE(PG8_SB(0, 1), b2 + hstep, voffB); PG8_STAGE(PG8_SA(0, 0), a2, voffA);
.Lp6t_w0b:
	s_waitcnt lgkmcnt(0)
	s_barrier
	s_setprio 1
	v_mfma_f32_16x16x32_bf16 v[60:63], v[156:159], v[188:191], v[60:63]
	v_mfma_f32_16x16x32_bf16 v[56:59], v[164:167], v[188:191], v[56:59]
	v_mfma_f32_16x16x32_bf16 v[88:91], v[156:159], v[196:199], v[88:91]
	v_mfma_f32_16x16x32_bf16 v[84:87], v[164:167], v[196:199], v[84:87]
	v_mfma_f32_16x16x32_bf16 v[108:111], v[156:159], v[204:207], v[108:111]
	v_mfma_f32_16x16x32_bf16 v[104:107], v[164:167], v[204:207], v[104:107]
	v_mfma_f32_16x16x32_bf16 v[124:127], v[156:159], v[212:215], v[124:127]
	v_mfma_f32_16x16x32_bf16 v[120:123], v[164:167], v[212:215], v[120:123]
	v_mfma_f32_16x16x32_bf16 v[60:63], v[160:163], v[192:195], v[60:63]
	v_mfma_f32_16x16x32_bf16 v[56:59], v[168:171], v[192:195], v[56:59]
	v_mfma_f32_16x16x32_bf16 v[88:91], v[160:163], v[200:203], v[88:91]
	v_mfma_f32_16x16x32_bf16 v[84:87], v[168:171], v[200:203], v[84:87]
	v_mfma_f32_16x16x32_bf16 v[108:111], v[160:163], v[208:211], v[108:111]
	v_mfma_f32_16x16x32_bf16 v[104:107], v[168:171], v[208:211], v[104:107]
	v_mfma_f32_16x16x32_bf16 v[124:127], v[160:163], v[216:219], v[124:127]
	v_mfma_f32_16x16x32_bf16 v[120:123], v[168:171], v[216:219], v[120:123]
	v_mfma_f32_16x16x32_bf16 v[36:39], v[172:175], v[188:191], v[36:39]
	v_mfma_f32_16x16x32_bf16 v[32:35], v[180:183], v[188:191], v[32:35]
	v_mfma_f32_16x16x32_bf16 v[68:71], v[172:175], v[196:199], v[68:71]
	v_mfma_f32_16x16x32_bf16 v[64:67], v[180:183], v[196:199], v[64:67]
	v_mfma_f32_16x16x32_bf16 v[100:103], v[172:175], v[204:207], v[100:103]
	v_mfma_f32_16x16x32_bf16 v[96:99], v[180:183], v[204:207], v[96:99]
	v_mfma_f32_16x16x32_bf16 v[116:119], v[172:175], v[212:215], v[116:119]
	v_mfma_f32_16x16x32_bf16 v[112:115], v[180:183], v[212:215], v[112:115]
	v_mfma_f32_16x16x32_bf16 v[36:39], v[176:179], v[192:195], v[36:39]
	v_mfma_f32_16x16x32_bf16 v[32:35], v[184:187], v[192:195], v[32:35]
	v_mfma_f32_16x16x32_bf16 v[68:71], v[176:179], v[200:203], v[68:71]
	v_mfma_f32_16x16x32_bf16 v[64:67], v[184:187], v[200:203], v[64:67]
	v_mfma_f32_16x16x32_bf16 v[100:103], v[176:179], v[208:211], v[100:103]
	v_mfma_f32_16x16x32_bf16 v[96:99], v[184:187], v[208:211], v[96:99]
	v_mfma_f32_16x16x32_bf16 v[116:119], v[176:179], v[216:219], v[116:119]
	v_mfma_f32_16x16x32_bf16 v[112:115], v[184:187], v[216:219], v[112:115]
	s_setprio 0
	s_barrier
	s_add_i32 s49, s43, s35
	v_lshl_add_u64 v[220:221], s[28:29], 0, v[130:131]
	s_mov_b32 m0, s49
	ds_read_b128 v[188:191], v154 offset:16384
	ds_read_b128 v[192:195], v154 offset:17408
	ds_read_b128 v[196:199], v154 offset:18432
	ds_read_b128 v[200:203], v154 offset:19456
	ds_read_b128 v[204:207], v154 offset:20480
	ds_read_b128 v[208:211], v154 offset:21504
	ds_read_b128 v[212:215], v154 offset:22528
	ds_read_b128 v[216:219], v154 offset:23552
	s_cmpk_eq_i32 s26, 0x700
	s_cbranch_scc1 .Lp6t_s1
	global_load_lds_dwordx4 v[220:221], off
	s_add_i32 m0, s49, 0x2000
	s_add_u32 s50, s28, 0x40000
	v_lshl_add_u64 v[222:223], s[28:29], 0, v[134:135]
	s_addc_u32 s51, s29, 0
	s_add_i32 s49, s44, s35
	global_load_lds_dwordx4 v[222:223], off
	v_lshl_add_u64 v[224:225], s[50:51], 0, v[130:131]
	s_mov_b32 m0, s49
	v_lshl_add_u64 v[226:227], s[30:31], 0, v[132:133]
	global_load_lds_dwordx4 v[224:225], off
	v_lshl_add_u64 v[224:225], s[50:51], 0, v[134:135]
	s_add_i32 m0, s49, 0x2000
	s_nop 0
	global_load_lds_dwordx4 v[224:225], off
	v_lshl_add_u64 v[224:225], s[30:31], 0, v[128:129]
	s_mov_b32 m0, s36
	s_nop 0
	global_load_lds_dwordx4 v[224:225], off
	s_mov_b32 m0, s37
	s_nop 0
	global_load_lds_dwordx4 v[226:227], off

; #define PG8_STAGE(bufoff, gbase, voff) do { _Pragma("unroll") for (int _i = 0; _i < 2; ++_i) \
;         __builtin_amdgcn_global_load_lds((const unsigned*)((const char*)(gbase) + (voff)[_i]), (PG8_LAS unsigned*)(lds + (bufoff) + ldsw + _i * 8192), 16, 0, 0); } while (0)
; #define PG8_LDA(dst, b, h) do { _Pragma("unroll") for (int m = 0; m < 4; ++m) _Pragma("unroll") for (int k = 0; k < 2; ++k) dst[m][k] = *(const PG8_LAS bf16x8*)(lds + PG8_SA(b, h) + aoff + m * 2048 + k * 1024); } while (0)
; #define PG8_LDB(dst, b, h) do { _Pragma("unroll") for (int n = 0; n < 2; ++n) _Pragma("unroll") for (int k = 0; k < 2; ++k) dst[n][k] = *(const PG8_LAS bf16x8*)(lds + PG8_SB(b, h) + boff + n * 2048 + k * 1024); } while (0)
; #define PG8_MMA(ai, bj, At, Bt) do { __builtin_amdgcn_s_setprio(1); _Pragma("unroll") for (int m = 0; m < 4; ++m) _Pragma("unroll") for (int n = 0; n < 2; ++n) _Pragma("unroll") for (int k = 0; k < 2; ++k) \
;         acc[ai][bj][m][n] = __builtin_amdgcn_mfma_f32_16x16x32_bf16(Bt[n][k], At[m][k], acc[ai][bj][m][n], 0, 0, 0); __builtin_amdgcn_s_setprio(0); } while (0)
; #define PG8_WAIT_V(n) asm volatile("s_waitcnt vmcnt(" #n ")" ::: "memory")
; #define PG8_WAIT_L(n) asm volatile("s_waitcnt lgkmcnt(" #n ")" ::: "memory")
; #define PG8_BAR __builtin_amdgcn_s_barrier()
; #define PG8_SCHED __builtin_amdgcn_sched_barrier(0)
; template <class Epi, class Sched, bool ALIGN_EPI = false, bool SP2 = false>
; __device__ __forceinline__ void gemm_phase(PG8_LAS unsigned char* lds, const Gemm g, const Sched& S, const Epi& E, int wid_in) {
;     ...
;             PG8_WAIT_V(8); PG8_WAIT_L(0); PG8_BAR; PG8_MMA(1, 0, At, B0); PG8_MMA(1, 1, At, B1); PG8_BAR; PG8_SCHED;
;             PG8_LDB(B0, 1, 0); PG8_LDB(B1, 1, 1); PG8_SCHED; PG8_LDA(At, 1, 0); PG8_STAGE(PG8_SA(0, 1), a2 + hstep, voffA);
.Lp6t_w1b:
	s_waitcnt lgkmcnt(0)
	s_barrier
	s_setprio 1
	v_mfma_f32_16x16x32_bf16 v[92:95], v[156:159], v[188:191], v[92:95]
	v_mfma_f32_16x16x32_bf16 v[80:83], v[164:167], v[188:191], v[80:83]
	v_mfma_f32_16x16x32_bf16 v[52:55], v[156:159], v[196:199], v[52:55]
	v_mfma_f32_16x16x32_bf16 v[48:51], v[164:167], v[196:199], v[48:51]
	v_mfma_f32_16x16x32_bf16 v[28:31], v[156:159], v[204:207], v[28:31]
	v_mfma_f32_16x16x32_bf16 v[24:27], v[164:167], v[204:207], v[24:27]
	v_mfma_f32_16x16x32_bf16 v[12:15], v[156:159], v[212:215], v[12:15]
	v_mfma_f32_16x16x32_bf16 v[8:11], v[164:167], v[212:215], v[8:11]
	v_mfma_f32_16x16x32_bf16 v[92:95], v[160:163], v[192:195], v[92:95]
	v_mfma_f32_16x16x32_bf16 v[80:83], v[168:171], v[192:195], v[80:83]
	v_mfma_f32_16x16x32_bf16 v[52:55], v[160:163], v[200:203], v[52:55]
	v_mfma_f32_16x16x32_bf16 v[48:51], v[168:171], v[200:203], v[48:51]
	v_mfma_f32_16x16x32_bf16 v[28:31], v[160:163], v[208:211], v[28:31]
	v_mfma_f32_16x16x32_bf16 v[24:27], v[168:171], v[208:211], v[24:27]
	v_mfma_f32_16x16x32_bf16 v[12:15], v[160:163], v[216:219], v[12:15]
	v_mfma_f32_16x16x32_bf16 v[8:11], v[168:171], v[216:219], v[8:11]
	v_mfma_f32_16x16x32_bf16 v[76:79], v[172:175], v[188:191], v[76:79]
	v_mfma_f32_16x16x32_bf16 v[72:75], v[180:183], v[188:191], v[72:75]
	v_mfma_f32_16x16x32_bf16 v[44:47], v[172:175], v[196:199], v[44:47]
	v_mfma_f32_16x16x32_bf16 v[40:43], v[180:183], v[196:199], v[40:43]
	v_mfma_f32_16x16x32_bf16 v[20:23], v[172:175], v[204:207], v[20:23]
	v_mfma_f32_16x16x32_bf16 v[16:19], v[180:183], v[204:207], v[16:19]
	v_mfma_f32_16x16x32_bf16 v[4:7], v[172:175], v[212:215], v[4:7]
	v_mfma_f32_16x16x32_bf16 v[0:3], v[180:183], v[212:215], v[0:3]
	v_mfma_f32_16x16x32_bf16 v[76:79], v[176:179], v[192:195], v[76:79]
	v_mfma_f32_16x16x32_bf16 v[72:75], v[184:187], v[192:195], v[72:75]
	v_mfma_f32_16x16x32_bf16 v[44:47], v[176:179], v[200:203], v[44:47]
	v_mfma_f32_16x16x32_bf16 v[40:43], v[184:187], v[200:203], v[40:43]
	v_mfma_f32_16x16x32_bf16 v[20:23], v[176:179], v[208:211], v[20:23]
	v_mfma_f32_16x16x32_bf16 v[16:19], v[184:187], v[208:211], v[16:19]
	v_mfma_f32_16x16x32_bf16 v[4:7], v[176:179], v[216:219], v[4:7]
	v_mfma_f32_16x16x32_bf16 v[0:3], v[184:187], v[216:219], v[0:3]
	s_setprio 0
	s_barrier
	s_add_i32 s49, 0, 0x18000
	v_add_u32_e32 v155, s49, v153
	s_add_i32 s50, 0, 0x1c000
	ds_read_b128 v[156:159], v155
	ds_read_b128 v[160:163], v155 offset:1024
	ds_read_b128 v[164:167], v155 offset:2048
	ds_read_b128 v[168:171], v155 offset:3072
	v_add_u32_e32 v155, s50, v153
	ds_read_b128 v[172:175], v155
	ds_read_b128 v[176:179], v155 offset:1024
	ds_read_b128 v[180:183], v155 offset:2048
	ds_read_b128 v[184:187], v155 offset:3072
	s_add_u32 s30, s30, 0x40000
	s_addc_u32 s31, s31, 0
	s_mov_b32 m0, s38
	v_lshl_add_u64 v[228:229], s[30:31], 0, v[128:129]
	ds_read_b128 v[188:191], v154 offset:32768
	ds_read_b128 v[192:195], v154 offset:33792
	ds_read_b128 v[196:199], v154 offset:34816
	ds_read_b128 v[200:203], v154 offset:35840
	ds_read_b128 v[204:207], v154 offset:36864
	ds_read_b128 v[208:211], v154 offset:37888
	ds_read_b128 v[212:215], v154 offset:38912
	ds_read_b128 v[216:219], v154 offset:39936
	s_cmpk_eq_i32 s26, 0x700
	s_cbranch_scc1 .Lp6t_s2
	global_load_lds_dwordx4 v[228:229], off
	v_lshl_add_u64 v[228:229], s[30:31], 0, v[132:133]
	s_mov_b32 m0, s39
	s_nop 0
	global_load_lds_dwordx4 v[228:229], off

; #define PG8_STAGE(bufoff, gbase, voff) do { _Pragma("unroll") for (int _i = 0; _i < 2; ++_i) \
;         __builtin_amdgcn_global_load_lds((const unsigned*)((const char*)(gbase) + (voff)[_i]), (PG8_LAS unsigned*)(lds + (bufoff) + ldsw + _i * 8192), 16, 0, 0); } while (0)
; #define PG8_LDA(dst, b, h) do { _Pragma("unroll") for (int m = 0; m < 4; ++m) _Pragma("unroll") for (int k = 0; k < 2; ++k) dst[m][k] = *(const PG8_LAS bf16x8*)(lds + PG8_SA(b, h) + aoff + m * 2048 + k * 1024); } while (0)
; #define PG8_MMA(ai, bj, At, Bt) do { __builtin_amdgcn_s_setprio(1); _Pragma("unroll") for (int m = 0; m < 4; ++m) _Pragma("unroll") for (int n = 0; n < 2; ++n) _Pragma("unroll") for (int k = 0; k < 2; ++k) \
;         acc[ai][bj][m][n] = __builtin_amdgcn_mfma_f32_16x16x32_bf16(Bt[n][k], At[m][k], acc[ai][bj][m][n], 0, 0, 0); __builtin_amdgcn_s_setprio(0); } while (0)
; #define PG8_WAIT_V(n) asm volatile("s_waitcnt vmcnt(" #n ")" ::: "memory")
; #define PG8_WAIT_L(n) asm volatile("s_waitcnt lgkmcnt(" #n ")" ::: "memory")
; #define PG8_BAR __builtin_amdgcn_s_barrier()
; #define PG8_SCHED __builtin_amdgcn_sched_barrier(0)
; template <class Epi, class Sched, bool ALIGN_EPI = false, bool SP2 = false>
; __device__ __forceinline__ void gemm_phase(PG8_LAS unsigned char* lds, const Gemm g, const Sched& S, const Epi& E, int wid_in) {
;     ...
;             PG8_WAIT_V(8); PG8_WAIT_L(0); PG8_BAR; PG8_MMA(0, 0, At, B0); PG8_MMA(0, 1, At, B1); PG8_BAR; PG8_SCHED;
;             PG8_LDA(At, 1, 1); PG8_STAGE(PG8_SB(1, 0), b3, voffB); PG8_STAGE(PG8_SB(1, 1), b3 + hstep, voffB); PG8_STAGE(PG8_SA(1, 0), a3, voffA);
.Lp6t_w2b:
	s_waitcnt lgkmcnt(0)
	s_barrier
	s_setprio 1
	v_mfma_f32_16x16x32_bf16 v[60:63], v[156:159], v[188:191], v[60:63]
	v_mfma_f32_16x16x32_bf16 v[56:59], v[164:167], v[188:191], v[56:59]
	v_mfma_f32_16x16x32_bf16 v[88:91], v[156:159], v[196:199], v[88:91]
	v_mfma_f32_16x16x32_bf16 v[84:87], v[164:167], v[196:199], v[84:87]
	v_mfma_f32_16x16x32_bf16 v[108:111], v[156:159], v[204:207], v[108:111]
	v_mfma_f32_16x16x32_bf16 v[104:107], v[164:167], v[204:207], v[104:107]
	v_mfma_f32_16x16x32_bf16 v[124:127], v[156:159], v[212:215], v[124:127]
	v_mfma_f32_16x16x32_bf16 v[120:123], v[164:167], v[212:215], v[120:123]
	v_mfma_f32_16x16x32_bf16 v[60:63], v[160:163], v[192:195], v[60:63]
	v_mfma_f32_16x16x32_bf16 v[56:59], v[168:171], v[192:195], v[56:59]
	v_mfma_f32_16x16x32_bf16 v[88:91], v[160:163], v[200:203], v[88:91]
	v_mfma_f32_16x16x32_bf16 v[84:87], v[168:171], v[200:203], v[84:87]
	v_mfma_f32_16x16x32_bf16 v[108:111], v[160:163], v[208:211], v[108:111]
	v_mfma_f32_16x16x32_bf16 v[104:107], v[168:171], v[208:211], v[104:107]
	v_mfma_f32_16x16x32_bf16 v[124:127], v[160:163], v[216:219], v[124:127]
	v_mfma_f32_16x16x32_bf16 v[120:123], v[168:171], v[216:219], v[120:123]
	v_mfma_f32_16x16x32_bf16 v[36:39], v[172:175], v[188:191], v[36:39]
	v_mfma_f32_16x16x32_bf16 v[32:35], v[180:183], v[188:191], v[32:35]
	v_mfma_f32_16x16x32_bf16 v[68:71], v[172:175], v[196:199], v[68:71]
	v_mfma_f32_16x16x32_bf16 v[64:67], v[180:183], v[196:199], v[64:67]
	v_mfma_f32_16x16x32_bf16 v[100:103], v[172:175], v[204:207], v[100:103]
	v_mfma_f32_16x16x32_bf16 v[96:99], v[180:183], v[204:207], v[96:99]
	v_mfma_f32_16x16x32_bf16 v[116:119], v[172:175], v[212:215], v[116:119]
	v_mfma_f32_16x16x32_bf16 v[112:115], v[180:183], v[212:215], v[112:115]
	v_mfma_f32_16x16x32_bf16 v[36:39], v[176:179], v[192:195], v[36:39]
	v_mfma_f32_16x16x32_bf16 v[32:35], v[184:187], v[192:195], v[32:35]
	v_mfma_f32_16x16x32_bf16 v[68:71], v[176:179], v[200:203], v[68:71]
	v_mfma_f32_16x16x32_bf16 v[64:67], v[184:187], v[200:203], v[64:67]
	v_mfma_f32_16x16x32_bf16 v[100:103], v[176:179], v[208:211], v[100:103]
	v_mfma_f32_16x16x32_bf16 v[96:99], v[184:187], v[208:211], v[96:99]
	v_mfma_f32_16x16x32_bf16 v[116:119], v[176:179], v[216:219], v[116:119]
	v_mfma_f32_16x16x32_bf16 v[112:115], v[184:187], v[216:219], v[112:115]
	s_setprio 0
	s_barrier
	s_add_i32 s30, s49, s35
	v_lshl_add_u64 v[220:221], v[220:221], 0, s[14:15]
	s_mov_b32 m0, s30
	ds_read_b128 v[188:191], v154 offset:49152
	ds_read_b128 v[192:195], v154 offset:50176
	ds_read_b128 v[196:199], v154 offset:51200
	ds_read_b128 v[200:203], v154 offset:52224
	ds_read_b128 v[204:207], v154 offset:53248
	ds_read_b128 v[208:211], v154 offset:54272
	ds_read_b128 v[212:215], v154 offset:55296
	ds_read_b128 v[216:219], v154 offset:56320
	s_cmpk_eq_i32 s26, 0x700
	s_cbranch_scc1 .Lp6t_s3
	global_load_lds_dwordx4 v[220:221], off
	s_add_i32 m0, s30, 0x2000
	s_add_u32 s28, s28, 0x40080
	v_lshl_add_u64 v[220:221], v[222:223], 0, s[14:15]
	s_addc_u32 s29, s29, 0
	s_add_i32 s30, s50, s35
	global_load_lds_dwordx4 v[220:221], off
	v_lshl_add_u64 v[220:221], s[28:29], 0, v[130:131]
	s_mov_b32 m0, s30
	s_nop 0
	global_load_lds_dwordx4 v[220:221], off
	v_lshl_add_u64 v[220:221], s[28:29], 0, v[134:135]
	s_add_i32 m0, s30, 0x2000
	s_nop 0
	global_load_lds_dwordx4 v[220:221], off
	v_lshl_add_u64 v[220:221], v[224:225], 0, s[14:15]
	s_mov_b32 m0, s41
	s_nop 0
	global_load_lds_dwordx4 v[220:221], off
	v_lshl_add_u64 v[220:221], v[226:227], 0, s[14:15]
	s_mov_b32 m0, s42
	s_nop 0
	global_load_lds_dwordx4 v[220:221], off

; #define PG8_MMA(ai, bj, At, Bt) do { __builtin_amdgcn_s_setprio(1); _Pragma("unroll") for (int m = 0; m < 4; ++m) _Pragma("unroll") for (int n = 0; n < 2; ++n) _Pragma("unroll") for (int k = 0; k < 2; ++k) \
;         acc[ai][bj][m][n] = __builtin_amdgcn_mfma_f32_16x16x32_bf16(Bt[n][k], At[m][k], acc[ai][bj][m][n], 0, 0, 0); __builtin_amdgcn_s_setprio(0); } while (0)
; #define PG8_WAIT_V(n) asm volatile("s_waitcnt vmcnt(" #n ")" ::: "memory")
; #define PG8_WAIT_L(n) asm volatile("s_waitcnt lgkmcnt(" #n ")" ::: "memory")
; #define PG8_BAR __builtin_amdgcn_s_barrier()
; #define PG8_SCHED __builtin_amdgcn_sched_barrier(0)
; template <class Epi, class Sched, bool ALIGN_EPI = false, bool SP2 = false>
; __device__ __forceinline__ void gemm_phase(PG8_LAS unsigned char* lds, const Gemm g, const Sched& S, const Epi& E, int wid_in) {
;     ...
;             PG8_WAIT_V(8); PG8_WAIT_L(0); PG8_BAR; PG8_MMA(1, 0, At, B0); PG8_MMA(1, 1, At, B1); PG8_BAR; PG8_SCHED;
;     ...
;         if constexpr (ALIGN_EPI) { if (wr == 0) PG8_BAR; }
;         if constexpr (!Epi::AFTER_DRAIN) { E(acc, cur, wr, wc, fr, fq); S.done(cur); }
;         if (!has_next) break;
; #pragma unroll
;         for (int a = 0; a < 2; ++a)
; #pragma unroll
;             for (int b = 0; b < 2; ++b)
; #pragma unroll
;                 for (int m = 0; m < 4; ++m)
; #pragma unroll
;                     for (int n = 0; n < 2; ++n) acc[a][b][m][n] = (f32x4){0.f, 0.f, 0.f, 0.f};
;         cur = nxt; cA = nA; cB = nB; ++ui;
.Lp6t_w3b:
	s_waitcnt lgkmcnt(0)
	s_barrier
	s_setprio 1
	v_mfma_f32_16x16x32_bf16 v[92:95], v[156:159], v[188:191], v[92:95]
	v_mfma_f32_16x16x32_bf16 v[80:83], v[164:167], v[188:191], v[80:83]
	v_mfma_f32_16x16x32_bf16 v[52:55], v[156:159], v[196:199], v[52:55]
	v_mfma_f32_16x16x32_bf16 v[48:51], v[164:167], v[196:199], v[48:51]
	v_mfma_f32_16x16x32_bf16 v[28:31], v[156:159], v[204:207], v[28:31]
	v_mfma_f32_16x16x32_bf16 v[24:27], v[164:167], v[204:207], v[24:27]
	v_mfma_f32_16x16x32_bf16 v[12:15], v[156:159], v[212:215], v[12:15]
	v_mfma_f32_16x16x32_bf16 v[8:11], v[164:167], v[212:215], v[8:11]
	v_mfma_f32_16x16x32_bf16 v[92:95], v[160:163], v[192:195], v[92:95]
	v_mfma_f32_16x16x32_bf16 v[80:83], v[168:171], v[192:195], v[80:83]
	v_mfma_f32_16x16x32_bf16 v[52:55], v[160:163], v[200:203], v[52:55]
	v_mfma_f32_16x16x32_bf16 v[48:51], v[168:171], v[200:203], v[48:51]
	v_mfma_f32_16x16x32_bf16 v[28:31], v[160:163], v[208:211], v[28:31]
	v_mfma_f32_16x16x32_bf16 v[24:27], v[168:171], v[208:211], v[24:27]
	v_mfma_f32_16x16x32_bf16 v[12:15], v[160:163], v[216:219], v[12:15]
	v_mfma_f32_16x16x32_bf16 v[8:11], v[168:171], v[216:219], v[8:11]
	v_mfma_f32_16x16x32_bf16 v[76:79], v[172:175], v[188:191], v[76:79]
	v_mfma_f32_16x16x32_bf16 v[72:75], v[180:183], v[188:191], v[72:75]
	v_mfma_f32_16x16x32_bf16 v[44:47], v[172:175], v[196:199], v[44:47]
	v_mfma_f32_16x16x32_bf16 v[40:43], v[180:183], v[196:199], v[40:43]
	v_mfma_f32_16x16x32_bf16 v[20:23], v[172:175], v[204:207], v[20:23]
	v_mfma_f32_16x16x32_bf16 v[16:19], v[180:183], v[204:207], v[16:19]
	v_mfma_f32_16x16x32_bf16 v[4:7], v[172:175], v[212:215], v[4:7]
	v_mfma_f32_16x16x32_bf16 v[0:3], v[180:183], v[212:215], v[0:3]
	v_mfma_f32_16x16x32_bf16 v[76:79], v[176:179], v[192:195], v[76:79]
	v_mfma_f32_16x16x32_bf16 v[72:75], v[184:187], v[192:195], v[72:75]
	v_mfma_f32_16x16x32_bf16 v[44:47], v[176:179], v[200:203], v[44:47]
	v_mfma_f32_16x16x32_bf16 v[40:43], v[184:187], v[200:203], v[40:43]
	v_mfma_f32_16x16x32_bf16 v[20:23], v[176:179], v[208:211], v[20:23]
	v_mfma_f32_16x16x32_bf16 v[16:19], v[184:187], v[208:211], v[16:19]
	v_mfma_f32_16x16x32_bf16 v[4:7], v[176:179], v[216:219], v[4:7]
	v_mfma_f32_16x16x32_bf16 v[0:3], v[184:187], v[216:219], v[0:3]
	s_setprio 0
	s_barrier
	s_add_i32 s48, s48, 2
	s_add_u32 s26, s26, 0x100
	s_addc_u32 s27, s27, 0
	s_cmp_gt_u32 s48, 13
	s_cbranch_scc0 .LBB0_986
	s_add_u32 s26, s23, 0xffffff00
	s_addc_u32 s27, s45, -1
	s_andn2_b64 vcc, exec, s[2:3]
	s_cbranch_vccnz .LBB0_977
	v_mov_b32_e32 v0, 0
	s_mov_b32 s6, s16
	s_mov_b32 s4, s18
	s_mov_b64 s[10:11], s[24:25]
	s_mov_b32 s40, s22
	v_mov_b32_e32 v1, v0
	v_mov_b32_e32 v2, v0
	v_mov_b32_e32 v3, v0
	v_mov_b32_e32 v4, v0
	v_mov_b32_e32 v5, v0
	v_mov_b32_e32 v6, v0
	v_mov_b32_e32 v7, v0
	v_mov_b32_e32 v16, v0
	v_mov_b32_e32 v17, v0
	v_mov_b32_e32 v18, v0
	v_mov_b32_e32 v19, v0
	v_mov_b32_e32 v20, v0
	v_mov_b32_e32 v21, v0
	v_mov_b32_e32 v22, v0
	v_mov_b32_e32 v23, v0
	v_mov_b32_e32 v40, v0
	v_mov_b32_e32 v41, v0
	v_mov_b32_e32 v42, v0
	v_mov_b32_e32 v43, v0
	v_mov_b32_e32 v44, v0
	v_mov_b32_e32 v45, v0
	v_mov_b32_e32 v46, v0
	v_mov_b32_e32 v47, v0
	v_mov_b32_e32 v72, v0
	v_mov_b32_e32 v73, v0
	v_mov_b32_e32 v74, v0
	v_mov_b32_e32 v75, v0
	v_mov_b32_e32 v76, v0
	v_mov_b32_e32 v77, v0
	v_mov_b32_e32 v78, v0
	v_mov_b32_e32 v79, v0
	v_mov_b32_e32 v8, v0
	v_mov_b32_e32 v9, v0
	v_mov_b32_e32 v10, v0
	v_mov_b32_e32 v11, v0
	v_mov_b32_e32 v12, v0
	v_mov_b32_e32 v13, v0
	v_mov_b32_e32 v14, v0
	v_mov_b32_e32 v15, v0
	v_mov_b32_e32 v24, v0
	v_mov_b32_e32 v25, v0
	v_mov_b32_e32 v26, v0
	v_mov_b32_e32 v27, v0
	v_mov_b32_e32 v28, v0
	v_mov_b32_e32 v29, v0
	v_mov_b32_e32 v30, v0
	v_mov_b32_e32 v31, v0
	v_mov_b32_e32 v48, v0
	v_mov_b32_e32 v49, v0
	v_mov_b32_e32 v50, v0
	v_mov_b32_e32 v51, v0
	v_mov_b32_e32 v52, v0
	v_mov_b32_e32 v53, v0
	v_mov_b32_e32 v54, v0
	v_mov_b32_e32 v55, v0
	v_mov_b32_e32 v80, v0
	v_mov_b32_e32 v81, v0
	v_mov_b32_e32 v82, v0
	v_mov_b32_e32 v83, v0
	v_mov_b32_e32 v92, v0
	v_mov_b32_e32 v93, v0
	v_mov_b32_e32 v94, v0
	v_mov_b32_e32 v95, v0
	v_mov_b32_e32 v112, v0
	v_mov_b32_e32 v113, v0
	v_mov_b32_e32 v114, v0
	v_mov_b32_e32 v115, v0
	v_mov_b32_e32 v116, v0
	v_mov_b32_e32 v117, v0
	v_mov_b32_e32 v118, v0
	v_mov_b32_e32 v119, v0
	v_mov_b32_e32 v96, v0
	v_mov_b32_e32 v97, v0
	v_mov_b32_e32 v98, v0
	v_mov_b32_e32 v99, v0
	v_mov_b32_e32 v100, v0
	v_mov_b32_e32 v101, v0
	v_mov_b32_e32 v102, v0
	v_mov_b32_e32 v103, v0
	v_mov_b32_e32 v64, v0
	v_mov_b32_e32 v65, v0
	v_mov_b32_e32 v66, v0
	v_mov_b32_e32 v67, v0
	v_mov_b32_e32 v68, v0
	v_mov_b32_e32 v69, v0
	v_mov_b32_e32 v70, v0
	v_mov_b32_e32 v71, v0
	v_mov_b32_e32 v32, v0
	v_mov_b32_e32 v33, v0
	v_mov_b32_e32 v34, v0
	v_mov_b32_e32 v35, v0
	v_mov_b32_e32 v36, v0
	v_mov_b32_e32 v37, v0
	v_mov_b32_e32 v38, v0
	v_mov_b32_e32 v39, v0
	v_mov_b32_e32 v120, v0
	v_mov_b32_e32 v121, v0
	v_mov_b32_e32 v122, v0
	v_mov_b32_e32 v123, v0
	v_mov_b32_e32 v124, v0
	v_mov_b32_e32 v125, v0
	v_mov_b32_e32 v126, v0
	v_mov_b32_e32 v127, v0
	v_mov_b32_e32 v104, v0
	v_mov_b32_e32 v105, v0
	v_mov_b32_e32 v106, v0
	v_mov_b32_e32 v107, v0
	v_mov_b32_e32 v108, v0
	v_mov_b32_e32 v109, v0
	v_mov_b32_e32 v110, v0
	v_mov_b32_e32 v111, v0
	v_mov_b32_e32 v84, v0
	v_mov_b32_e32 v85, v0
	v_mov_b32_e32 v86, v0
	v_mov_b32_e32 v87, v0
	v_mov_b32_e32 v88, v0
	v_mov_b32_e32 v89, v0
	v_mov_b32_e32 v90, v0
	v_mov_b32_e32 v91, v0
	v_mov_b32_e32 v56, v0
	v_mov_b32_e32 v57, v0
	v_mov_b32_e32 v58, v0
	v_mov_b32_e32 v59, v0
	v_mov_b32_e32 v60, v0
	v_mov_b32_e32 v61, v0
	v_mov_b32_e32 v62, v0
	v_mov_b32_e32 v63, v0
	s_andn2_b64 vcc, exec, s[0:1]
	s_cbranch_vccnz .LBB0_978
